# v112 + 4 M-tiles x 8 N-tiles per round also in the out-projection GEMM3 and memory-PV GEMM7 (each A tile read once per XCD)
# speedup vs baseline: 1.0135x; 1.0044x over previous
; template <int GI>
; __device__ __forceinline__ bool sched_next(unsigned char* ws, int i, int G, int c, GUnit& u) {
;     ...
;         constexpr int nwg = d.nM * d.nN;
;         if (L >= nwg) return false;
;         int wgid = L;
;         { constexpr int q = nwg / 8, r = nwg % 8; const int xcd = wgid % 8, off = wgid / 8; wgid = (xcd < r ? xcd * (q + 1) : r * (q + 1) + (xcd - r) * q) + off; }
;         constexpr int nig = 8 * d.nN; const int gid = wgid / nig, fm = gid * 8, gsz = (d.nM - fm) < 8 ? (d.nM - fm) : 8;
;         const int pm = fm + ((wgid % nig) % gsz), pn = (wgid % nig) / gsz;
; template <int GI>
; __device__ __forceinline__ void gemm_phase(LAS unsigned char* lds, unsigned char* ws, int G, int cblk) {
;     ...
;     const int tid = tid_, wid = __builtin_amdgcn_readfirstlane(tid >> 6), lane = tid & 63, wr = wid >> 2, wc = wid & 3, fr = lane & 15, fq = lane >> 4;
;     constexpr int K = g.K, nt = K / BK, lda = g.lda, ldb = g.ldb;
;     unsigned voffA[2], voffB[2];
; #pragma unroll
;     for (int i = 0; i < 2; ++i) { int R, C; stage_rc(tid * 16 + i * 8192, R, C); const int Rb = (R & ~31) + perm32(R & 31);
;         voffA[i] = (unsigned)(R * lda + C) * 2u; voffB[i] = (unsigned)(Rb * ldb + C) * 2u; }
;     const size_t kstep = (size_t)(BK * 2);
;     const size_t hstepA = (size_t)HALF * lda * 2, hstepB = (size_t)HALF * ldb * 2;
;     const unsigned ldsw = (unsigned)wid * 1024u;
;     const int aoff = lds_byte(wr * 64 + fr, fq * 8), boff = lds_byte(wc * 32 + fr, fq * 8);
;     ...
;     GUnit cur, nxt; int ui = 0;
;     if (!sched_next<GI>(ws, 0, G, cblk, cur)) return;
;     f32x4 acc[2][2][4][2];
; #pragma unroll
;     for (int a = 0; a < 2; ++a)
; #pragma unroll
;         for (int b = 0; b < 2; ++b)
; #pragma unroll
;             for (int m = 0; m < 4; ++m)
; #pragma unroll
;                 for (int n = 0; n < 2; ++n) acc[a][b][m][n] = (f32x4){0.f, 0.f, 0.f, 0.f};
;     bf16x8 At[4][2], B0[2][2], B1[2][2];
;     const char* cA = cur.A; const char* cB = cur.B;
;     PG8_STAGE(PG8_SB(0, 0), cB, voffB); PG8_STAGE(PG8_SB(0, 1), cB + hstepB, voffB); PG8_STAGE(PG8_SA(0, 0), cA, voffA); PG8_STAGE(PG8_SA(0, 1), cA + hstepA, voffA);
;     if (wr == 1) PG8_BAR;
;     PG8_WAIT_V(2); PG8_BAR;
;     PG8_STAGE(PG8_SB(1, 0), cB + kstep, voffB); PG8_STAGE(PG8_SA(1, 0), cA + kstep, voffA); PG8_STAGE(PG8_SB(1, 1), cB + hstepB + kstep, voffB);
;     PG8_WAIT_V(6); PG8_BAR;
.LBB0_388:
	v_ashrrev_i32_e32 v1, 31, v8
	v_lshrrev_b32_e32 v1, 26, v1
	v_add_u32_e32 v1, v8, v1
	v_ashrrev_i32_e32 v9, 6, v1
	v_bfe_i32 v1, v8, 27, 1
	v_lshlrev_b32_e32 v0, 4, v8
	v_lshrrev_b32_e32 v1, 22, v1
	v_add_u32_e32 v1, v0, v1
	v_and_b32_e32 v1, 0xfffffc00, v1
	v_sub_u32_e32 v1, v0, v1
	v_lshrrev_b32_e32 v2, 4, v1
	v_bitop3_b32 v1, v2, v1, 32 bitop3:0x6c
	v_ashrrev_i32_e32 v3, 31, v1
	v_lshrrev_b32_e32 v3, 26, v3
	v_add_u32_e32 v3, v1, v3
	v_lshlrev_b32_e32 v2, 3, v9
	v_ashrrev_i32_e32 v10, 6, v3
	v_and_b32_e32 v3, 0xc0, v3
	v_and_b32_e32 v2, -16, v2
	v_sub_u32_e32 v1, v1, v3
	v_mov_b32_e32 v3, 1
	v_add_u32_e32 v2, v10, v2
	v_ashrrev_i16_sdwa v1, v3, sext(v1) dst_sel:DWORD dst_unused:UNUSED_PAD src0_sel:DWORD src1_sel:BYTE_0
	s_ashr_i32 s3, s0, 3
	v_lshlrev_b32_e32 v4, 5, v9
	v_bfe_i32 v11, v1, 0, 16
	v_lshlrev_b32_e32 v1, 1, v2
	v_lshrrev_b32_e32 v5, 2, v2
	v_and_b32_e32 v6, 3, v10
	s_mov_b32 s0, 0xfffe0
	v_and_b32_e32 v4, 32, v4
	v_and_b32_e32 v1, 24, v1
	v_and_b32_e32 v5, 4, v5
	v_and_or_b32 v6, v2, s0, v6
	v_or3_b32 v1, v6, v5, v1
	v_add_lshl_u32 v4, v4, v11, 1
	v_add_u32_e32 v0, 0x2000, v0
	v_lshl_add_u32 v130, v1, 12, v4
	v_ashrrev_i32_e32 v1, 31, v0
	v_lshrrev_b32_e32 v1, 22, v1
	v_add_u32_e32 v1, v0, v1
	s_add_i32 s1, s1, s3
	s_and_b32 s3, s1, 3
	s_bfe_u32 s5, s1, 0x10005
	s_lshl_b32 s5, s5, 2
	s_or_b32 s3, s3, s5
	s_bfe_u32 s5, s1, 0x30002
	s_lshl_b32 s5, s5, 3
	s_or_b32 s3, s3, s5
	s_andn2_b32 s1, s1, 63
	s_or_b32 s1, s1, s3
	v_ashrrev_i32_e32 v12, 10, v1
	s_ashr_i32 s3, s1, 31
	v_mul_i32_i24_e32 v1, 0x400, v12
	s_lshr_b32 s3, s3, 26
	v_sub_u32_e32 v0, v0, v1
	s_add_i32 s3, s1, s3
	v_lshrrev_b32_e32 v1, 4, v0
	s_ashr_i32 s5, s3, 6
	s_andn2_b32 s3, s3, 63
	v_bitop3_b32 v0, v1, v0, 32 bitop3:0x6c
	s_sub_i32 s1, s1, s3
	v_lshl_add_u32 v128, v2, 12, v4
	v_ashrrev_i32_e32 v2, 31, v0
	s_bfe_i32 s3, s1, 0x80000
	v_lshrrev_b32_e32 v2, 26, v2
	s_bfe_u32 s3, s3, 0x3000c
	v_add_u32_e32 v2, v0, v2
	s_add_i32 s3, s1, s3
	v_lshlrev_b32_e32 v1, 3, v12
	v_ashrrev_i32_e32 v13, 6, v2
	v_and_b32_e32 v2, 0xc0, v2
	s_bfe_i32 s6, s3, 0x80000
	s_and_b32 s3, s3, 0xf8
	v_and_b32_e32 v1, -16, v1
	v_sub_u32_e32 v0, v0, v2
	s_sub_i32 s1, s1, s3
	s_ashr_i32 s4, s14, 6
	v_add_u32_e32 v1, v13, v1
	v_ashrrev_i16_sdwa v0, v3, sext(v0) dst_sel:DWORD dst_unused:UNUSED_PAD src0_sel:DWORD src1_sel:BYTE_0
	v_and_b32_e32 v3, 3, v13
	s_lshl_b32 s5, s5, 3
	s_sext_i32_i16 s6, s6
	s_sext_i32_i8 s1, s1
	v_and_or_b32 v3, v1, s0, v3
	s_ashr_i32 s15, s14, 8
	s_lshl_b32 s0, s4, 10
	s_lshr_b32 s6, s6, 3
	s_add_i32 s8, s5, s1
	s_add_u32 s1, s28, 0x2e000000
	s_addc_u32 s3, s29, 0
	s_ashr_i32 s9, s8, 31
	s_lshl_b64 s[8:9], s[8:9], 20
	s_add_u32 s46, s1, s8
	s_addc_u32 s47, s3, s9
	s_bfe_i64 s[12:13], s[6:7], 0x100000
	s_lshl_b64 s[6:7], s[12:13], 20
	s_add_u32 s48, s58, s6
	v_lshlrev_b32_e32 v4, 5, v12
	v_bfe_i32 v14, v0, 0, 16
	v_lshlrev_b32_e32 v0, 1, v1
	v_lshrrev_b32_e32 v2, 2, v1
	s_addc_u32 s49, s59, s7
	s_add_i32 s16, s0, 0
	v_and_b32_e32 v4, 32, v4
	v_and_b32_e32 v0, 24, v0
	v_and_b32_e32 v2, 4, v2
	s_add_i32 m0, s16, 0x10000
	v_or3_b32 v0, v3, v2, v0
	v_add_lshl_u32 v2, v4, v14, 1
	global_load_lds_dwordx4 v130, s[48:49]
	s_add_i32 m0, s16, 0x12000
	v_lshl_add_u32 v134, v0, 12, v2
	s_add_u32 s6, s48, 0x80000
	global_load_lds_dwordx4 v134, s[48:49]
	s_addc_u32 s7, s49, 0
	s_add_i32 m0, s16, 0x14000
	s_add_i32 s17, s16, 0x2000
	global_load_lds_dwordx4 v130, s[6:7]
	s_add_i32 m0, s16, 0x16000
	v_lshl_add_u32 v132, v1, 12, v2
	global_load_lds_dwordx4 v134, s[6:7]
	s_mov_b32 m0, s16
	s_add_u32 s6, s46, 0x80000
	global_load_lds_dwordx4 v128, s[46:47]
	s_mov_b32 m0, s17
	s_addc_u32 s7, s47, 0
	s_add_i32 s22, s16, 0x4000
	global_load_lds_dwordx4 v132, s[46:47]
	s_mov_b32 m0, s22
	s_add_i32 s23, s16, 0x6000
	global_load_lds_dwordx4 v128, s[6:7]
	s_mov_b32 m0, s23
	v_mov_b32_e32 v137, 0
	global_load_lds_dwordx4 v132, s[6:7]
	v_mov_b32_e32 v131, v137
	v_mov_b32_e32 v135, v137
	v_mov_b32_e32 v129, v137
	v_mov_b32_e32 v133, v137
	s_cmp_eq_u32 s15, 1
	s_mov_b32 s5, 0
	v_lshl_add_u64 v[6:7], s[48:49], 0, v[130:131]
	v_lshl_add_u64 v[4:5], s[48:49], 0, v[134:135]
	v_lshl_add_u64 v[0:1], s[46:47], 0, v[128:129]
	s_cselect_b64 s[6:7], -1, 0
	s_cmp_lg_u32 s15, 1
	v_lshl_add_u64 v[2:3], s[46:47], 0, v[132:133]
	s_cbranch_scc1 .LBB0_390
	s_barrier

; template <int GI>
; __device__ __forceinline__ bool sched_next(unsigned char* ws, int i, int G, int c, GUnit& u) {
;     ...
;         constexpr int nwg = d.nM * d.nN;
;         if (L >= nwg) return false;
;         int wgid = L;
;         { constexpr int q = nwg / 8, r = nwg % 8; const int xcd = wgid % 8, off = wgid / 8; wgid = (xcd < r ? xcd * (q + 1) : r * (q + 1) + (xcd - r) * q) + off; }
;         constexpr int nig = 8 * d.nN; const int gid = wgid / nig, fm = gid * 8, gsz = (d.nM - fm) < 8 ? (d.nM - fm) : 8;
;         const int pm = fm + ((wgid % nig) % gsz), pn = (wgid % nig) / gsz;
;         u.A = (const char*)ws + d.A + (size_t)pm * d.a_tile;
;         u.B = (const char*)ws + d.B + (size_t)(pm >> 4) * d.b_batch + (size_t)pn * d.b_tile;
;         u.C = (char*)ws + d.C + (size_t)pm * d.c_rt + (size_t)pn * d.c_ct;
; template <int GI>
; __device__ __forceinline__ void gemm_phase(LAS unsigned char* lds, unsigned char* ws, int G, int cblk) {
;     ...
;         const bool has_next = sched_next<GI>(ws, ui + 1, G, cblk, nxt);
;         const char* nA = has_next ? nxt.A : cA; const char* nB = has_next ? nxt.B : cB;
.LBB0_398:
	s_ashr_i32 s14, s19, 3
	s_add_i32 s14, s40, s14
	s_and_b32 s15, s14, 3
	s_bfe_u32 s19, s14, 0x10005
	s_lshl_b32 s19, s19, 2
	s_or_b32 s15, s15, s19
	s_bfe_u32 s19, s14, 0x30002
	s_lshl_b32 s19, s19, 3
	s_or_b32 s15, s15, s19
	s_andn2_b32 s14, s14, 63
	s_or_b32 s14, s14, s15
	s_ashr_i32 s15, s14, 31
	s_lshr_b32 s15, s15, 26
	s_add_i32 s15, s14, s15
	s_ashr_i32 s19, s15, 6
	s_and_b32 s15, s15, 0xffc0
	s_sub_i32 s15, s14, s15
	s_bfe_i32 s14, s15, 0x80000
	s_bfe_u32 s14, s14, 0x3000c
	s_add_i32 s34, s15, s14
	s_bfe_i32 s14, s34, 0x80000
	s_and_b32 s34, s34, 0xf8
	s_sub_i32 s15, s15, s34
	s_lshl_b32 s19, s19, 3
	s_sext_i32_i8 s15, s15
	s_add_i32 s40, s19, s15
	s_sext_i32_i16 s14, s14
	s_ashr_i32 s41, s40, 31
	s_lshr_b32 s14, s14, 3
	s_lshl_b64 s[44:45], s[40:41], 20
	s_add_u32 s40, s1, s44
	s_addc_u32 s41, s3, s45
	s_bfe_i64 s[14:15], s[14:15], 0x100000
	s_lshl_b64 s[42:43], s[14:15], 20
	s_add_u32 s42, s58, s42
	s_addc_u32 s43, s59, s43
	s_add_u32 s19, s24, s44
	s_addc_u32 s34, s25, s45
	s_lshl_b64 s[14:15], s[14:15], 9
	s_add_u32 s44, s19, s14
	s_addc_u32 s45, s34, s15

; template <int GI>
; __device__ __forceinline__ bool sched_next(unsigned char* ws, int i, int G, int c, GUnit& u) {
;     ...
;         constexpr int nwg = d.nM * d.nN;
;         if (L >= nwg) return false;
;         int wgid = L;
;         { constexpr int q = nwg / 8, r = nwg % 8; const int xcd = wgid % 8, off = wgid / 8; wgid = (xcd < r ? xcd * (q + 1) : r * (q + 1) + (xcd - r) * q) + off; }
;         constexpr int nig = 8 * d.nN; const int gid = wgid / nig, fm = gid * 8, gsz = (d.nM - fm) < 8 ? (d.nM - fm) : 8;
;         const int pm = fm + ((wgid % nig) % gsz), pn = (wgid % nig) / gsz;
; template <int GI>
; __device__ __forceinline__ void gemm_phase(LAS unsigned char* lds, unsigned char* ws, int G, int cblk) {
;     ...
;     const int tid = tid_, wid = __builtin_amdgcn_readfirstlane(tid >> 6), lane = tid & 63, wr = wid >> 2, wc = wid & 3, fr = lane & 15, fq = lane >> 4;
;     constexpr int K = g.K, nt = K / BK, lda = g.lda, ldb = g.ldb;
;     unsigned voffA[2], voffB[2];
; #pragma unroll
;     for (int i = 0; i < 2; ++i) { int R, C; stage_rc(tid * 16 + i * 8192, R, C); const int Rb = (R & ~31) + perm32(R & 31);
;         voffA[i] = (unsigned)(R * lda + C) * 2u; voffB[i] = (unsigned)(Rb * ldb + C) * 2u; }
;     const size_t kstep = (size_t)(BK * 2);
;     const size_t hstepA = (size_t)HALF * lda * 2, hstepB = (size_t)HALF * ldb * 2;
;     const unsigned ldsw = (unsigned)wid * 1024u;
;     const int aoff = lds_byte(wr * 64 + fr, fq * 8), boff = lds_byte(wc * 32 + fr, fq * 8);
;     ...
;     GUnit cur, nxt; int ui = 0;
;     if (!sched_next<GI>(ws, 0, G, cblk, cur)) return;
;     f32x4 acc[2][2][4][2];
; #pragma unroll
;     for (int a = 0; a < 2; ++a)
; #pragma unroll
;         for (int b = 0; b < 2; ++b)
; #pragma unroll
;             for (int m = 0; m < 4; ++m)
; #pragma unroll
;                 for (int n = 0; n < 2; ++n) acc[a][b][m][n] = (f32x4){0.f, 0.f, 0.f, 0.f};
;     bf16x8 At[4][2], B0[2][2], B1[2][2];
;     const char* cA = cur.A; const char* cB = cur.B;
;     PG8_STAGE(PG8_SB(0, 0), cB, voffB); PG8_STAGE(PG8_SB(0, 1), cB + hstepB, voffB); PG8_STAGE(PG8_SA(0, 0), cA, voffA); PG8_STAGE(PG8_SA(0, 1), cA + hstepA, voffA);
;     if (wr == 1) PG8_BAR;
;     PG8_WAIT_V(2); PG8_BAR;
;     PG8_STAGE(PG8_SB(1, 0), cB + kstep, voffB); PG8_STAGE(PG8_SA(1, 0), cA + kstep, voffA); PG8_STAGE(PG8_SB(1, 1), cB + hstepB + kstep, voffB);
;     PG8_WAIT_V(6); PG8_BAR;
.LBB0_685:
	v_ashrrev_i32_e32 v1, 31, v8
	v_lshrrev_b32_e32 v1, 26, v1
	v_add_u32_e32 v1, v8, v1
	v_ashrrev_i32_e32 v9, 6, v1
	v_bfe_i32 v1, v8, 27, 1
	v_lshlrev_b32_e32 v0, 4, v8
	v_lshrrev_b32_e32 v1, 22, v1
	v_add_u32_e32 v1, v0, v1
	v_and_b32_e32 v1, 0xfffffc00, v1
	v_sub_u32_e32 v1, v0, v1
	v_lshrrev_b32_e32 v2, 4, v1
	v_bitop3_b32 v1, v2, v1, 32 bitop3:0x6c
	v_ashrrev_i32_e32 v3, 31, v1
	v_lshrrev_b32_e32 v3, 26, v3
	v_add_u32_e32 v3, v1, v3
	v_lshlrev_b32_e32 v2, 3, v9
	v_ashrrev_i32_e32 v10, 6, v3
	v_and_b32_e32 v3, 0xc0, v3
	v_and_b32_e32 v2, -16, v2
	v_sub_u32_e32 v1, v1, v3
	v_mov_b32_e32 v3, 1
	v_add_u32_e32 v2, v10, v2
	v_ashrrev_i16_sdwa v1, v3, sext(v1) dst_sel:DWORD dst_unused:UNUSED_PAD src0_sel:DWORD src1_sel:BYTE_0
	s_ashr_i32 s7, s0, 3
	v_lshlrev_b32_e32 v4, 5, v9
	v_bfe_i32 v11, v1, 0, 16
	v_lshlrev_b32_e32 v1, 1, v2
	v_lshrrev_b32_e32 v5, 2, v2
	v_and_b32_e32 v6, 3, v10
	s_mov_b32 s0, 0x1fffe0
	v_and_b32_e32 v4, 32, v4
	v_and_b32_e32 v1, 24, v1
	v_and_b32_e32 v5, 4, v5
	v_and_or_b32 v6, v2, s0, v6
	v_or3_b32 v1, v6, v5, v1
	v_add_lshl_u32 v4, v4, v11, 1
	v_add_u32_e32 v0, 0x2000, v0
	v_lshl_add_u32 v132, v1, 11, v4
	v_ashrrev_i32_e32 v1, 31, v0
	v_lshrrev_b32_e32 v1, 22, v1
	v_add_u32_e32 v1, v0, v1
	s_add_i32 s1, s1, s7
	s_and_b32 s7, s1, 3
	s_bfe_u32 s8, s1, 0x10005
	s_lshl_b32 s8, s8, 2
	s_or_b32 s7, s7, s8
	s_bfe_u32 s8, s1, 0x30002
	s_lshl_b32 s8, s8, 3
	s_or_b32 s7, s7, s8
	s_andn2_b32 s1, s1, 63
	s_or_b32 s1, s1, s7
	v_ashrrev_i32_e32 v12, 10, v1
	s_ashr_i32 s7, s1, 31
	v_mul_i32_i24_e32 v1, 0x400, v12
	s_lshr_b32 s7, s7, 26
	v_sub_u32_e32 v0, v0, v1
	s_add_i32 s7, s1, s7
	v_lshrrev_b32_e32 v1, 4, v0
	s_ashr_i32 s8, s7, 6
	s_andn2_b32 s7, s7, 63
	v_bitop3_b32 v0, v1, v0, 32 bitop3:0x6c
	s_sub_i32 s1, s1, s7
	v_lshl_add_u32 v130, v2, 11, v4
	v_ashrrev_i32_e32 v2, 31, v0
	s_bfe_i32 s7, s1, 0x80000
	v_lshrrev_b32_e32 v2, 26, v2
	s_bfe_u32 s7, s7, 0x3000c
	v_add_u32_e32 v2, v0, v2
	s_add_i32 s7, s1, s7
	v_lshlrev_b32_e32 v1, 3, v12
	v_ashrrev_i32_e32 v13, 6, v2
	v_and_b32_e32 v2, 0xc0, v2
	s_lshl_b32 s9, s8, 3
	s_bfe_i32 s8, s7, 0x80000
	s_and_b32 s7, s7, 0xf8
	v_and_b32_e32 v1, -16, v1
	v_sub_u32_e32 v0, v0, v2
	s_sub_i32 s1, s1, s7
	s_ashr_i32 s6, s16, 6
	v_add_u32_e32 v1, v13, v1
	v_ashrrev_i16_sdwa v0, v3, sext(v0) dst_sel:DWORD dst_unused:UNUSED_PAD src0_sel:DWORD src1_sel:BYTE_0
	v_and_b32_e32 v3, 3, v13
	s_sext_i32_i16 s8, s8
	s_sext_i32_i8 s1, s1
	v_and_or_b32 v3, v1, s0, v3
	s_ashr_i32 s17, s16, 8
	s_lshl_b32 s0, s6, 10
	s_lshr_b32 s8, s8, 3
	s_add_i32 s12, s9, s1
	s_add_u32 s1, s28, 0x26000000
	s_addc_u32 s22, s29, 0
	s_ashr_i32 s13, s12, 31
	s_lshl_b64 s[14:15], s[12:13], 19
	s_add_u32 s44, s1, s14
	s_addc_u32 s45, s22, s15
	s_add_u32 s23, s28, 0xbc00000
	s_addc_u32 s24, s29, 0
	s_ashr_i32 s14, s12, 4
	s_ashr_i32 s15, s14, 31
	s_lshl_b64 s[14:15], s[14:15], 22
	s_add_u32 s7, s23, s14
	s_addc_u32 s18, s24, s15
	s_bfe_i64 s[14:15], s[8:9], 0x100000
	s_lshl_b64 s[8:9], s[14:15], 19
	s_add_u32 s46, s7, s8
	v_lshlrev_b32_e32 v4, 5, v12
	v_bfe_i32 v14, v0, 0, 16
	v_lshlrev_b32_e32 v0, 1, v1
	v_lshrrev_b32_e32 v2, 2, v1
	s_addc_u32 s47, s18, s9
	s_add_i32 s25, s0, 0
	v_and_b32_e32 v4, 32, v4
	v_and_b32_e32 v0, 24, v0
	v_and_b32_e32 v2, 4, v2
	s_add_i32 m0, s25, 0x10000
	v_or3_b32 v0, v3, v2, v0
	v_add_lshl_u32 v2, v4, v14, 1
	global_load_lds_dwordx4 v132, s[46:47]
	s_add_i32 m0, s25, 0x12000
	v_lshl_add_u32 v136, v0, 11, v2
	s_add_u32 s8, s46, 0x40000
	global_load_lds_dwordx4 v136, s[46:47]
	s_addc_u32 s9, s47, 0
	s_add_i32 m0, s25, 0x14000
	s_add_i32 s26, s25, 0x2000
	global_load_lds_dwordx4 v132, s[8:9]
	s_add_i32 m0, s25, 0x16000
	v_lshl_add_u32 v134, v1, 11, v2
	global_load_lds_dwordx4 v136, s[8:9]
	s_mov_b32 m0, s25
	s_add_u32 s8, s44, 0x40000
	global_load_lds_dwordx4 v130, s[44:45]
	s_mov_b32 m0, s26
	s_addc_u32 s9, s45, 0
	s_add_i32 s27, s25, 0x4000
	global_load_lds_dwordx4 v134, s[44:45]
	s_mov_b32 m0, s27
	s_add_i32 s33, s25, 0x6000
	global_load_lds_dwordx4 v130, s[8:9]
	s_mov_b32 m0, s33
	v_mov_b32_e32 v139, 0
	global_load_lds_dwordx4 v134, s[8:9]
	v_mov_b32_e32 v133, v139
	v_mov_b32_e32 v137, v139
	v_mov_b32_e32 v131, v139
	v_mov_b32_e32 v135, v139
	s_cmp_eq_u32 s17, 1
	s_mov_b32 s7, 0
	v_lshl_add_u64 v[6:7], s[46:47], 0, v[132:133]
	v_lshl_add_u64 v[4:5], s[46:47], 0, v[136:137]
	v_lshl_add_u64 v[0:1], s[44:45], 0, v[130:131]
	s_cselect_b64 s[8:9], -1, 0
	s_cmp_lg_u32 s17, 1
	v_lshl_add_u64 v[2:3], s[44:45], 0, v[134:135]
	s_cbranch_scc1 .LBB0_687
	s_barrier

; template <int GI>
; __device__ __forceinline__ bool sched_next(unsigned char* ws, int i, int G, int c, GUnit& u) {
;     ...
;         constexpr int nwg = d.nM * d.nN;
;         if (L >= nwg) return false;
;         int wgid = L;
;         { constexpr int q = nwg / 8, r = nwg % 8; const int xcd = wgid % 8, off = wgid / 8; wgid = (xcd < r ? xcd * (q + 1) : r * (q + 1) + (xcd - r) * q) + off; }
;         constexpr int nig = 8 * d.nN; const int gid = wgid / nig, fm = gid * 8, gsz = (d.nM - fm) < 8 ? (d.nM - fm) : 8;
;         const int pm = fm + ((wgid % nig) % gsz), pn = (wgid % nig) / gsz;
;         u.A = (const char*)ws + d.A + (size_t)pm * d.a_tile;
;         u.B = (const char*)ws + d.B + (size_t)(pm >> 4) * d.b_batch + (size_t)pn * d.b_tile;
;         u.C = (char*)ws + d.C + (size_t)pm * d.c_rt + (size_t)pn * d.c_ct;
; template <int GI>
; __device__ __forceinline__ void gemm_phase(LAS unsigned char* lds, unsigned char* ws, int G, int cblk) {
;     ...
;         const bool has_next = sched_next<GI>(ws, ui + 1, G, cblk, nxt);
;         const char* nA = has_next ? nxt.A : cA; const char* nB = has_next ? nxt.B : cB;
.LBB0_695:
	s_ashr_i32 s16, s19, 3
	s_add_i32 s16, s38, s16
	s_and_b32 s17, s16, 3
	s_bfe_u32 s19, s16, 0x10005
	s_lshl_b32 s19, s19, 2
	s_or_b32 s17, s17, s19
	s_bfe_u32 s19, s16, 0x30002
	s_lshl_b32 s19, s19, 3
	s_or_b32 s17, s17, s19
	s_andn2_b32 s16, s16, 63
	s_or_b32 s16, s16, s17
	s_ashr_i32 s17, s16, 31
	s_lshr_b32 s17, s17, 26
	s_add_i32 s17, s16, s17
	s_ashr_i32 s19, s17, 6
	s_and_b32 s17, s17, 0xffc0
	s_sub_i32 s17, s16, s17
	s_bfe_i32 s16, s17, 0x80000
	s_bfe_u32 s16, s16, 0x3000c
	s_add_i32 s34, s17, s16
	s_bfe_i32 s16, s34, 0x80000
	s_and_b32 s34, s34, 0xf8
	s_sub_i32 s17, s17, s34
	s_lshl_b32 s19, s19, 3
	s_sext_i32_i8 s17, s17
	s_add_i32 s42, s19, s17
	s_sext_i32_i16 s16, s16
	s_ashr_i32 s43, s42, 31
	s_lshr_b32 s16, s16, 3
	s_lshl_b64 s[38:39], s[42:43], 19
	s_add_u32 s38, s1, s38
	s_addc_u32 s39, s22, s39
	s_ashr_i32 s40, s42, 4
	s_ashr_i32 s41, s40, 31
	s_lshl_b64 s[40:41], s[40:41], 22
	s_add_u32 s19, s23, s40
	s_addc_u32 s34, s24, s41
	s_bfe_i64 s[16:17], s[16:17], 0x100000
	s_lshl_b64 s[40:41], s[16:17], 19
	s_add_u32 s40, s19, s40
	s_addc_u32 s41, s34, s41
	s_lshl_b64 s[42:43], s[42:43], 20
	s_add_u32 s19, s35, s42
	s_addc_u32 s34, s50, s43
	s_lshl_b64 s[16:17], s[16:17], 9
	s_add_u32 s42, s19, s16
	s_addc_u32 s43, s34, s17
